# C tile loop head: tile DMA issued from MFMA gaps, vote-word reads issued first and consumed before the first MFMA behind lgkmcnt(6), K reads right after the barrier, hipcc flag glue removed
# baseline (speedup 1.0000x reference)
; DI float max3f(float a, float b, float c) { float r; asm("v_max3_f32 %0, %1, %2, %3" : "=v"(r) : "v"(a), "v"(b), "v"(c)); return r; }
; DI float swapmax(float m) { auto rr = __builtin_amdgcn_permlane32_swap(__float_as_uint(m), __float_as_uint(m), false, false); return fmaxf(__uint_as_float(rr[0]), __uint_as_float(rr[1])); }
; #define SBAR() __builtin_amdgcn_sched_barrier(0)
; #define MF(a_, b_, c_) __builtin_amdgcn_mfma_f32_32x32x16_bf16(a_, b_, c_, 0, 0, 0)
; template <int KIND> DI void attn_unit(const Params& P, int b, int h, int qb, char* shm, float lam, bool dry = false) {
;     ...
;     f32x16 pa0, pa1, pb0, pb1;
;     bf16x8 kf[4], x0, x1;
;     ATT_KLD(0, 0); ATT_XLD(0);
;     pa0 = MF(kf[0], qr[0], negm); pa1 = MF(kf[1], qr[0], negm); pa0 = MF(kf[2], qr[1], pa0); pa1 = MF(kf[3], qr[1], pa1);
;     SBAR(); ATT_KLD(0, 1); SBAR();
;     pa0 = MF(kf[0], qr[2], pa0); pa1 = MF(kf[1], qr[2], pa1); pa0 = MF(kf[2], qr[3], pa0); pa1 = MF(kf[3], qr[3], pa1);
;     if (KIND == 2) { pa0 = MF(x0, ones, pa0); pa1 = MF(x1, ones, pa1); }
;     ATT_FIX(pa0, pa1, ATT_TILE(0));
;     { float rm = max3f(pa0[0], pa0[1], pa1[0]), rm2 = max3f(pa0[2], pa0[3], pa1[1]); rm = max3f(rm, pa1[2], pa1[3]);
; #pragma unroll
;       for (int r = 4; r < 16; r += 4) { rm = max3f(rm, pa0[r], pa0[r + 1]); rm2 = max3f(rm2, pa0[r + 2], pa0[r + 3]); rm = max3f(rm, pa1[r], pa1[r + 1]); rm2 = max3f(rm2, pa1[r + 2], pa1[r + 3]); }
;       rm = swapmax(max3f(rm, rm2, rm2)); ATT_DECIDE(pa0, pa1, rm); }
;     for (int i = 0; i < nt_eff; ++i) {
;         ATT_STEP_BAR(i);
;         const int sn = (sc == 3 * SLOT) ? 0 : sc + SLOT;
;         const lds_cptr vp = shm3 + sc + 16384 + vlane;
;         bf16x8 vq[4]; bf16x8 pw[4]; u32x4 w0, w1; float sacc = 0.f;
;     ...
;         ATT_KLD(sn, 0); ATT_XLD(sn);
;         SBAR();
;     ...
;         G1(pb0 = MF(kf[0], qr[0], negm), 0, w0, 0);  G1(pb1 = MF(kf[1], qr[0], negm), 2, w0, 1);
;         G1(pb0 = MF(kf[2], qr[1], pb0), 4, w0, 2);   G1(pb1 = MF(kf[3], qr[1], pb1), 6, w0, 3);
;         ATT_KLD(sn, 1);
;         SBAR();
;         G1(pb0 = MF(kf[0], qr[2], pb0), 8, w1, 0);   G1(pb1 = MF(kf[1], qr[2], pb1), 10, w1, 1);
;         LDV(0); SBAR();
;         G1(pb0 = MF(kf[2], qr[3], pb0), 12, w1, 2);
;         LDV(1); SBAR();
;         G1(pb1 = MF(kf[3], qr[3], pb1), 14, w1, 3);
;         LDV(2); SBAR();
.LBB0_348:
	s_cmp_le_u32 s35, s33
	s_cselect_b32 s27, 1, 0
	s_add_i32 s31, s35, 1
	s_cmp_eq_u32 s35, 0
	s_cbranch_scc1 .Lcv_s1
	s_and_b32 s18, s25, 24
	s_lshl_b32 s18, s18, 2
	s_add_i32 s18, s18, 0x23240
	v_mov_b32_e32 v88, s18
	ds_read_b128 v[84:87], v88
	ds_read_b128 v[88:91], v88 offset:16
.Lcv_s1:
	s_add_i32 s18, s34, 0x8400
	s_cmp_lg_u32 s34, 0x18c00
	s_cselect_b32 s29, s18, 0
	s_add_i32 s18, s29, 0
	v_add_u32_e32 v72, s18, v168
	v_add_u32_e32 v186, v72, v167
	ds_read_b128 v[100:103], v186
	ds_read_b128 v[174:177], v186 offset:512
	ds_read_b128 v[178:181], v186 offset:2048
	ds_read_b128 v[182:185], v186 offset:2560
	ds_read_b128 v[190:193], v72 offset:32768
	ds_read_b128 v[196:199], v72 offset:33280
	v_exp_f32_e32 v116, v116
	v_exp_f32_e32 v117, v117
	s_nop 0
	v_cvt_pk_bf16_f32 v152, v116, v117
	v_add_f32_e32 v72, 0, v116
	v_add_f32_e32 v72, v117, v72
	v_exp_f32_e32 v118, v118
	v_exp_f32_e32 v119, v119
	v_add_f32_e32 v72, v72, v118
	v_add_f32_e32 v72, v119, v72
	v_cvt_pk_bf16_f32 v153, v118, v119
	v_exp_f32_e32 v120, v120
	v_exp_f32_e32 v121, v121
	v_add_f32_e32 v72, v72, v120
	v_add_f32_e32 v187, v121, v72
	v_cvt_pk_bf16_f32 v154, v120, v121
	s_cmp_eq_u32 s35, 0
	s_cbranch_scc1 .Lcv_s2
	s_waitcnt lgkmcnt(6)
	v_and_b32_e32 v84, v84, v85
	v_and_b32_e32 v84, v84, v86
	v_and_b32_e32 v84, v84, v87
	v_and_b32_e32 v84, v84, v88
	v_and_b32_e32 v84, v84, v89
	v_and_b32_e32 v84, v84, v90
	v_and_b32_e32 v84, v84, v91
	v_cmp_eq_u32_e32 vcc, 0, v84
	v_mov_b32_e32 v84, s31
	s_nop 0
	v_cndmask_b32_e32 v173, v84, v173, vcc
.Lcv_s2:
	s_waitcnt lgkmcnt(5)
	v_mfma_f32_32x32x16_bf16 v[84:99], v[100:103], v[144:147], v[20:35]
	v_exp_f32_e32 v122, v122
	v_exp_f32_e32 v123, v123
	s_waitcnt lgkmcnt(4)
	v_mfma_f32_32x32x16_bf16 v[100:115], v[174:177], v[144:147], v[20:35]
	s_add_i32 s18, s34, 0
	v_exp_f32_e32 v124, v124
	v_exp_f32_e32 v125, v125
	s_waitcnt lgkmcnt(3)
	v_mfma_f32_32x32x16_bf16 v[84:99], v[178:181], v[140:143], v[84:99]
	v_add3_u32 v68, s18, v170, v171
	v_add_f32_e32 v72, v187, v122
	v_cvt_pk_bf16_f32 v148, v124, v125
	v_add_u32_e32 v164, v68, v172
	s_waitcnt lgkmcnt(0)
	v_add_f32_e32 v187, v123, v72
	v_cvt_pk_bf16_f32 v155, v122, v123
	v_mfma_f32_32x32x16_bf16 v[100:115], v[182:185], v[140:143], v[100:115]
	ds_read_b128 v[72:75], v186 offset:4096
	ds_read_b128 v[80:83], v186 offset:4608
	ds_read_b128 v[174:177], v186 offset:6144
	ds_read_b128 v[178:181], v186 offset:6656
	s_waitcnt lgkmcnt(3)
	v_mfma_f32_32x32x16_bf16 v[84:99], v[72:75], v[136:139], v[84:99]
	s_cmp_eq_u32 s27, 0
	s_cbranch_scc1 .Lct1_nd0
	s_lshl_b64 s[38:39], s[20:21], 13
	s_add_i32 m0, s41, s30
	v_lshl_add_u64 v[182:183], v[156:157], 0, s[38:39]
	global_load_lds_dwordx4 v[182:183], off
.Lct1_nd0:
	v_add_f32_e32 v72, v187, v124
	v_add_f32_e32 v72, v125, v72
	s_waitcnt lgkmcnt(2)
	v_mfma_f32_32x32x16_bf16 v[100:115], v[80:83], v[136:139], v[100:115]
	v_exp_f32_e32 v126, v126
	v_exp_f32_e32 v127, v127
	v_add_f32_e32 v72, v72, v126
	v_add_f32_e32 v80, v127, v72
	v_cvt_pk_bf16_f32 v149, v126, v127
	ds_read_b64_tr_b16 v[72:73], v164 offset:16384
	ds_read_b64_tr_b16 v[74:75], v164 offset:16896
	s_waitcnt lgkmcnt(3)
	v_mfma_f32_32x32x16_bf16 v[84:99], v[174:177], v[132:135], v[84:99]
	v_exp_f32_e32 v128, v128
	v_exp_f32_e32 v129, v129
	v_add_f32_e32 v80, v80, v128
	v_add_f32_e32 v174, v129, v80
	v_cvt_pk_bf16_f32 v150, v128, v129
	ds_read_b64_tr_b16 v[80:81], v164 offset:20480
	ds_read_b64_tr_b16 v[82:83], v164 offset:20992
	s_waitcnt lgkmcnt(4)
	v_mfma_f32_32x32x16_bf16 v[100:115], v[178:181], v[132:135], v[100:115]
	s_cmp_eq_u32 s27, 0
	s_cbranch_scc1 .Lct1_nd1
	s_lshl_b64 s[38:39], s[20:21], 12
	s_add_i32 m0, s23, s30
	v_lshl_add_u64 v[182:183], v[158:159], 0, s[38:39]
	global_load_lds_dwordx4 v[182:183], off
; #define SBAR() __builtin_amdgcn_sched_barrier(0)
; #define PIN(x) asm volatile("" : "+v"(x))
; #define MF(a_, b_, c_) __builtin_amdgcn_mfma_f32_32x32x16_bf16(a_, b_, c_, 0, 0, 0)
; #define LDV(j_) do { if ((j_) < 4 * NDB) { const lds_cptr a_ = vp + ((j_) % NDB) * 4096 + ((j_) / NDB) * 1024; const s16x4 lo_ = vtr(a_), hi_ = vtr(a_ + 512); \
;             vq[(j_) & 3] = (bf16x8){lo_[0], lo_[1], lo_[2], lo_[3], hi_[0], hi_[1], hi_[2], hi_[3]}; } } while (0)
; #define PVM(j_) o[(j_) % NDB] = MF(vq[(j_) & 3], pw[(j_) / NDB], o[(j_) % NDB])
; #define E4(a_, W_, j_) do { pa1[a_] = EX(pa1[a_]); pa1[a_ + 1] = EX(pa1[a_ + 1]); sacc += pa1[a_]; sacc += pa1[a_ + 1]; W_[j_] = cvtpk(pa1[a_], pa1[a_ + 1]); } while (0)
; template <int KIND> DI void attn_unit(const Params& P, int b, int h, int qb, char* shm, float lam, bool dry = false) {
;     ...
;         if (KIND == 2) { pb0 = MF(x0, ones, pb0); pb1 = MF(x1, ones, pb1); }
;         pw[0] = __builtin_bit_cast(bf16x8, w0); pw[1] = __builtin_bit_cast(bf16x8, w1);
;     ...
;         if (NDB == 4) {
;             LDV(3); PVM(0); E4(0, w0, 0); PIN(pa1); PIN(sacc); PIN(w0); SBAR();
;             LDV(4); PVM(1); E4(2, w0, 1); PIN(pa1); PIN(sacc); PIN(w0); SBAR();
;             LDV(5); PVM(2); E4(4, w0, 2); PIN(pa1); PIN(sacc); PIN(w0); SBAR();
;             LDV(6); PVM(3); E4(6, w0, 3); PIN(pa1); PIN(sacc); PIN(w0); SBAR();
;             LDV(7); PVM(4); E4(8, w1, 0); PIN(pa1); PIN(sacc); PIN(w1); SBAR();
;             LDV(8); PVM(5); E4(10, w1, 1); PIN(pa1); PIN(sacc); PIN(w1); SBAR();
;             LDV(9); PVM(6); E4(12, w1, 2); PIN(pa1); PIN(sacc); PIN(w1); SBAR();
;             LDV(10); PVM(7); E4(14, w1, 3); PIN(pa1); PIN(sacc); PIN(w1); SBAR();
;         } else {
;             LDV(3); PVM(0); E4(0, w0, 0); E4(2, w0, 1); PIN(pa1); PIN(sacc); PIN(w0); SBAR();
;             LDV(4); PVM(1); E4(4, w0, 2); E4(6, w0, 3); PIN(pa1); PIN(sacc); PIN(w0); SBAR();
;             LDV(5); PVM(2); E4(8, w1, 0); E4(10, w1, 1); PIN(pa1); PIN(sacc); PIN(w1); SBAR();
;             LDV(6); PVM(3); E4(12, w1, 2); E4(14, w1, 3); PIN(pa1); PIN(sacc); PIN(w1); SBAR();
;         }
;     ...
;         pw[2] = __builtin_bit_cast(bf16x8, w0); pw[3] = __builtin_bit_cast(bf16x8, w1);
;         lsum += sacc;
;         ATT_FIX(pb0, pb1, ATT_TILE(i + 1));
.Lct1_nd1:
	v_exp_f32_e32 v130, v130
	v_exp_f32_e32 v131, v131
	v_add_f32_e32 v151, v174, v130
	v_add_f32_e32 v174, v131, v151
	v_cvt_pk_bf16_f32 v151, v130, v131
	ds_read_b64_tr_b16 v[124:125], v164 offset:17408
	ds_read_b64_tr_b16 v[126:127], v164 offset:17920
	v_mfma_f32_32x32x16_bf16 v[84:99], v[190:193], v[0:3], v[84:99]
	v_exp_f32_e32 v4, v4
	v_exp_f32_e32 v5, v5
	v_exp_f32_e32 v6, v6
	v_exp_f32_e32 v7, v7
	v_cvt_pk_bf16_f32 v190, v4, v5
	v_mfma_f32_32x32x16_bf16 v[100:115], v[196:199], v[0:3], v[100:115]
	ds_read_b64_tr_b16 v[68:69], v164 offset:21504
	ds_read_b64_tr_b16 v[70:71], v164 offset:22016
	s_waitcnt lgkmcnt(6)
	v_mfma_f32_32x32x16_bf16 v[52:67], v[72:75], v[152:155], v[52:67]
	v_add_f32_e32 v72, v4, v174
	v_add_f32_e32 v76, v5, v72
	v_add_f32_e32 v73, v6, v76
	v_add_f32_e32 v76, v7, v73
	v_cvt_pk_bf16_f32 v191, v6, v7
	v_exp_f32_e32 v8, v8
	v_exp_f32_e32 v9, v9
	s_waitcnt lgkmcnt(4)
	v_mfma_f32_32x32x16_bf16 v[36:51], v[80:83], v[152:155], v[36:51]
	s_cmp_eq_u32 s27, 0
	s_cbranch_scc1 .Lct1_nd2
	s_and_b64 vcc, exec, s[42:43]
	s_cbranch_vccnz .Lct1_nd2
	s_lshl_b64 s[38:39], s[20:21], 10
	s_add_i32 m0, s30, 0x8000
	v_lshl_add_u64 v[182:183], v[160:161], 0, s[38:39]
	global_load_lds_dwordx4 v[182:183], off
.Lct1_nd2:
	v_exp_f32_e32 v10, v10
	v_exp_f32_e32 v11, v11
	v_add_f32_e32 v74, v76, v8
	ds_read_b64_tr_b16 v[116:117], v164 offset:18432
	ds_read_b64_tr_b16 v[118:119], v164 offset:18944
	v_add_f32_e32 v75, v9, v74
	v_add_f32_e32 v75, v10, v75
	v_cvt_pk_bf16_f32 v192, v8, v9
	v_add_f32_e32 v76, v11, v75
	v_cvt_pk_bf16_f32 v193, v10, v11
	v_exp_f32_e32 v12, v12
	s_waitcnt lgkmcnt(4)
	v_mfma_f32_32x32x16_bf16 v[52:67], v[124:127], v[148:151], v[52:67]
	v_exp_f32_e32 v13, v13
	v_exp_f32_e32 v14, v14
	ds_read_b64_tr_b16 v[120:121], v164 offset:22528
	ds_read_b64_tr_b16 v[122:123], v164 offset:23040
	v_exp_f32_e32 v15, v15
	v_add_f32_e32 v72, v76, v12
	v_add_f32_e32 v76, v13, v72
	v_cvt_pk_bf16_f32 v152, v12, v13
	v_add_f32_e32 v73, v14, v76
	v_add_f32_e32 v76, v15, v73
	v_cvt_pk_bf16_f32 v153, v14, v15
	s_waitcnt lgkmcnt(4)
	v_mfma_f32_32x32x16_bf16 v[36:51], v[68:71], v[148:151], v[36:51]
	v_exp_f32_e32 v16, v16
	v_exp_f32_e32 v17, v17
	v_exp_f32_e32 v18, v18
	v_exp_f32_e32 v19, v19
	ds_read_b64_tr_b16 v[124:125], v164 offset:19456
	ds_read_b64_tr_b16 v[126:127], v164 offset:19968
	v_add_f32_e32 v68, v76, v16
	v_add_f32_e32 v68, v17, v68
	v_cvt_pk_bf16_f32 v154, v16, v17
	v_cvt_pk_bf16_f32 v155, v18, v19
	v_add_f32_e32 v68, v18, v68
	v_add_f32_e32 v68, v19, v68
	s_cmp_lg_u32 s22, s35
	s_cbranch_scc1 .LBB0_357
	v_cndmask_b32_e64 v4, v84, v245, s[48:49]
	v_cndmask_b32_e64 v100, v100, v245, s[50:51]
	v_cndmask_b32_e64 v85, v245, v85, s[52:53]
	v_cndmask_b32_e64 v84, v4, v84, s[52:53]
	v_cndmask_b32_e64 v101, v101, v245, s[54:55]
	v_cndmask_b32_e64 v86, v86, v245, s[56:57]
	v_cndmask_b32_e64 v102, v102, v245, s[58:59]
	v_cndmask_b32_e64 v87, v87, v245, s[60:61]
	v_cndmask_b32_e64 v103, v103, v245, s[62:63]
	v_cndmask_b32_e64 v88, v88, v245, s[64:65]
	v_cndmask_b32_e64 v104, v104, v245, s[66:67]
	v_cndmask_b32_e64 v89, v89, v245, s[68:69]
	v_cndmask_b32_e64 v105, v105, v245, s[70:71]
	v_cndmask_b32_e64 v90, v90, v245, s[72:73]
	v_cndmask_b32_e64 v106, v106, v245, s[74:75]
	v_cndmask_b32_e64 v91, v91, v245, s[76:77]
	v_cndmask_b32_e64 v107, v107, v245, s[78:79]
	v_cndmask_b32_e64 v92, v92, v245, s[80:81]
	v_cndmask_b32_e64 v108, v108, v245, s[82:83]
	v_cndmask_b32_e64 v93, v93, v245, s[84:85]
	v_cndmask_b32_e64 v109, v109, v245, s[86:87]
	v_cndmask_b32_e64 v94, v94, v245, s[88:89]
	v_cndmask_b32_e64 v110, v110, v245, s[90:91]
	v_cndmask_b32_e64 v95, v95, v245, s[92:93]
	v_cndmask_b32_e64 v111, v111, v245, s[94:95]
	v_cndmask_b32_e64 v96, v96, v245, s[96:97]
	v_cndmask_b32_e64 v112, v112, v245, s[4:5]
	v_cndmask_b32_e64 v97, v97, v245, s[6:7]
	v_cndmask_b32_e64 v113, v113, v245, s[8:9]
	v_cndmask_b32_e64 v98, v98, v245, s[10:11]
	v_cndmask_b32_e64 v114, v114, v245, s[12:13]
	v_cndmask_b32_e64 v99, v99, v245, s[14:15]
	v_cndmask_b32_e64 v115, v115, v245, s[16:17]

; DI float max3f(float a, float b, float c) { float r; asm("v_max3_f32 %0, %1, %2, %3" : "=v"(r) : "v"(a), "v"(b), "v"(c)); return r; }
; DI float swapmax(float m) { auto rr = __builtin_amdgcn_permlane32_swap(__float_as_uint(m), __float_as_uint(m), false, false); return fmaxf(__uint_as_float(rr[0]), __uint_as_float(rr[1])); }
; #define SBAR() __builtin_amdgcn_sched_barrier(0)
; #define MF(a_, b_, c_) __builtin_amdgcn_mfma_f32_32x32x16_bf16(a_, b_, c_, 0, 0, 0)
; template <int KIND> DI void attn_unit(const Params& P, int b, int h, int qb, char* shm, float lam, bool dry = false) {
;     ...
;     f32x16 pa0, pa1, pb0, pb1;
;     bf16x8 kf[4], x0, x1;
;     ATT_KLD(0, 0); ATT_XLD(0);
;     pa0 = MF(kf[0], qr[0], negm); pa1 = MF(kf[1], qr[0], negm); pa0 = MF(kf[2], qr[1], pa0); pa1 = MF(kf[3], qr[1], pa1);
;     SBAR(); ATT_KLD(0, 1); SBAR();
;     pa0 = MF(kf[0], qr[2], pa0); pa1 = MF(kf[1], qr[2], pa1); pa0 = MF(kf[2], qr[3], pa0); pa1 = MF(kf[3], qr[3], pa1);
;     if (KIND == 2) { pa0 = MF(x0, ones, pa0); pa1 = MF(x1, ones, pa1); }
;     ATT_FIX(pa0, pa1, ATT_TILE(0));
;     { float rm = max3f(pa0[0], pa0[1], pa1[0]), rm2 = max3f(pa0[2], pa0[3], pa1[1]); rm = max3f(rm, pa1[2], pa1[3]);
; #pragma unroll
;       for (int r = 4; r < 16; r += 4) { rm = max3f(rm, pa0[r], pa0[r + 1]); rm2 = max3f(rm2, pa0[r + 2], pa0[r + 3]); rm = max3f(rm, pa1[r], pa1[r + 1]); rm2 = max3f(rm2, pa1[r + 2], pa1[r + 3]); }
;       rm = swapmax(max3f(rm, rm2, rm2)); ATT_DECIDE(pa0, pa1, rm); }
;     for (int i = 0; i < nt_eff; ++i) {
;         ATT_STEP_BAR(i);
;         const int sn = (sc == 3 * SLOT) ? 0 : sc + SLOT;
;         const lds_cptr vp = shm3 + sc + 16384 + vlane;
;         bf16x8 vq[4]; bf16x8 pw[4]; u32x4 w0, w1; float sacc = 0.f;
;     ...
;         ATT_KLD(sn, 0); ATT_XLD(sn);
;         SBAR();
;     ...
;         G1(pb0 = MF(kf[0], qr[0], negm), 0, w0, 0);  G1(pb1 = MF(kf[1], qr[0], negm), 2, w0, 1);
;         G1(pb0 = MF(kf[2], qr[1], pb0), 4, w0, 2);   G1(pb1 = MF(kf[3], qr[1], pb1), 6, w0, 3);
;         ATT_KLD(sn, 1);
;         SBAR();
;         G1(pb0 = MF(kf[0], qr[2], pb0), 8, w1, 0);   G1(pb1 = MF(kf[1], qr[2], pb1), 10, w1, 1);
;         LDV(0); SBAR();
;         G1(pb0 = MF(kf[2], qr[3], pb0), 12, w1, 2);
;         LDV(1); SBAR();
;         G1(pb1 = MF(kf[3], qr[3], pb1), 14, w1, 3);
;         LDV(2); SBAR();
.Lct2_348:
	s_cmp_le_u32 s35, s33
	s_cselect_b32 s27, 1, 0
	s_add_i32 s31, s35, 1
	s_add_i32 s18, s34, 0x8400
	s_cmp_lg_u32 s34, 0x18c00
	s_cselect_b32 s29, s18, 0
	s_add_i32 s18, s29, 0
	v_add_u32_e32 v116, s18, v168
	v_add_u32_e32 v186, v116, v167
	ds_read_b128 v[4:7], v186
	ds_read_b128 v[174:177], v186 offset:512
	ds_read_b128 v[178:181], v186 offset:2048
	ds_read_b128 v[182:185], v186 offset:2560
	ds_read_b128 v[190:193], v116 offset:32768
	ds_read_b128 v[196:199], v116 offset:33280
	v_exp_f32_e32 v84, v84
	v_exp_f32_e32 v85, v85
	s_nop 0
	v_cvt_pk_bf16_f32 v152, v84, v85
	v_add_f32_e32 v116, 0, v84
	v_add_f32_e32 v116, v85, v116
	v_exp_f32_e32 v86, v86
	v_exp_f32_e32 v87, v87
	v_add_f32_e32 v116, v116, v86
	v_add_f32_e32 v116, v87, v116
	v_cvt_pk_bf16_f32 v153, v86, v87
	v_exp_f32_e32 v88, v88
	v_exp_f32_e32 v89, v89
	v_add_f32_e32 v116, v116, v88
	v_add_f32_e32 v187, v89, v116
	v_cvt_pk_bf16_f32 v154, v88, v89
	s_waitcnt lgkmcnt(5)
	v_mfma_f32_32x32x16_bf16 v[116:131], v[4:7], v[144:147], v[20:35]
	v_exp_f32_e32 v90, v90
	v_exp_f32_e32 v91, v91
	s_waitcnt lgkmcnt(4)
	v_mfma_f32_32x32x16_bf16 v[4:19], v[174:177], v[144:147], v[20:35]
	s_add_i32 s18, s34, 0
	v_exp_f32_e32 v92, v92
	v_exp_f32_e32 v93, v93
	s_waitcnt lgkmcnt(3)
	v_mfma_f32_32x32x16_bf16 v[116:131], v[178:181], v[140:143], v[116:131]
	v_add3_u32 v68, s18, v170, v171
	v_add_f32_e32 v72, v187, v90
	v_cvt_pk_bf16_f32 v148, v92, v93
	v_add_u32_e32 v164, v68, v172
	s_waitcnt lgkmcnt(0)
	v_add_f32_e32 v187, v91, v72
	v_cvt_pk_bf16_f32 v155, v90, v91
	v_mfma_f32_32x32x16_bf16 v[4:19], v[182:185], v[140:143], v[4:19]
	ds_read_b128 v[72:75], v186 offset:4096
	ds_read_b128 v[80:83], v186 offset:4608
	ds_read_b128 v[174:177], v186 offset:6144
	ds_read_b128 v[178:181], v186 offset:6656
	s_waitcnt lgkmcnt(3)
	v_mfma_f32_32x32x16_bf16 v[116:131], v[72:75], v[136:139], v[116:131]
	s_cmp_eq_u32 s27, 0
	s_cbranch_scc1 .Lct2x_nd0
	s_lshl_b64 s[38:39], s[20:21], 13
	s_add_i32 m0, s41, s30
	v_lshl_add_u64 v[182:183], v[156:157], 0, s[38:39]
	global_load_lds_dwordx4 v[182:183], off
.Lct2x_nd0:
	v_add_f32_e32 v72, v187, v92
	v_add_f32_e32 v72, v93, v72
	s_waitcnt lgkmcnt(2)
	v_mfma_f32_32x32x16_bf16 v[4:19], v[80:83], v[136:139], v[4:19]
	v_exp_f32_e32 v94, v94
	v_exp_f32_e32 v95, v95
	v_add_f32_e32 v72, v72, v94
	v_add_f32_e32 v80, v95, v72
	v_cvt_pk_bf16_f32 v149, v94, v95
	ds_read_b64_tr_b16 v[72:73], v164 offset:16384
	ds_read_b64_tr_b16 v[74:75], v164 offset:16896
	s_waitcnt lgkmcnt(3)
	v_mfma_f32_32x32x16_bf16 v[116:131], v[174:177], v[132:135], v[116:131]
	v_exp_f32_e32 v96, v96
	v_exp_f32_e32 v97, v97
	v_add_f32_e32 v80, v80, v96
	v_add_f32_e32 v174, v97, v80
	v_cvt_pk_bf16_f32 v150, v96, v97
	ds_read_b64_tr_b16 v[80:81], v164 offset:20480
	ds_read_b64_tr_b16 v[82:83], v164 offset:20992
	s_waitcnt lgkmcnt(4)
	v_mfma_f32_32x32x16_bf16 v[4:19], v[178:181], v[132:135], v[4:19]
	s_cmp_eq_u32 s27, 0
	s_cbranch_scc1 .Lct2x_nd1
	s_lshl_b64 s[38:39], s[20:21], 12
	s_add_i32 m0, s23, s30
	v_lshl_add_u64 v[182:183], v[158:159], 0, s[38:39]
	global_load_lds_dwordx4 v[182:183], off
; #define SBAR() __builtin_amdgcn_sched_barrier(0)
; #define PIN(x) asm volatile("" : "+v"(x))
; #define MF(a_, b_, c_) __builtin_amdgcn_mfma_f32_32x32x16_bf16(a_, b_, c_, 0, 0, 0)
; #define LDV(j_) do { if ((j_) < 4 * NDB) { const lds_cptr a_ = vp + ((j_) % NDB) * 4096 + ((j_) / NDB) * 1024; const s16x4 lo_ = vtr(a_), hi_ = vtr(a_ + 512); \
;             vq[(j_) & 3] = (bf16x8){lo_[0], lo_[1], lo_[2], lo_[3], hi_[0], hi_[1], hi_[2], hi_[3]}; } } while (0)
; #define PVM(j_) o[(j_) % NDB] = MF(vq[(j_) & 3], pw[(j_) / NDB], o[(j_) % NDB])
; #define E4(a_, W_, j_) do { pa1[a_] = EX(pa1[a_]); pa1[a_ + 1] = EX(pa1[a_ + 1]); sacc += pa1[a_]; sacc += pa1[a_ + 1]; W_[j_] = cvtpk(pa1[a_], pa1[a_ + 1]); } while (0)
; template <int KIND> DI void attn_unit(const Params& P, int b, int h, int qb, char* shm, float lam, bool dry = false) {
;     ...
;         if (KIND == 2) { pb0 = MF(x0, ones, pb0); pb1 = MF(x1, ones, pb1); }
;         pw[0] = __builtin_bit_cast(bf16x8, w0); pw[1] = __builtin_bit_cast(bf16x8, w1);
;     ...
;         if (NDB == 4) {
;             LDV(3); PVM(0); E4(0, w0, 0); PIN(pa1); PIN(sacc); PIN(w0); SBAR();
;             LDV(4); PVM(1); E4(2, w0, 1); PIN(pa1); PIN(sacc); PIN(w0); SBAR();
;             LDV(5); PVM(2); E4(4, w0, 2); PIN(pa1); PIN(sacc); PIN(w0); SBAR();
;             LDV(6); PVM(3); E4(6, w0, 3); PIN(pa1); PIN(sacc); PIN(w0); SBAR();
;             LDV(7); PVM(4); E4(8, w1, 0); PIN(pa1); PIN(sacc); PIN(w1); SBAR();
;             LDV(8); PVM(5); E4(10, w1, 1); PIN(pa1); PIN(sacc); PIN(w1); SBAR();
;             LDV(9); PVM(6); E4(12, w1, 2); PIN(pa1); PIN(sacc); PIN(w1); SBAR();
;             LDV(10); PVM(7); E4(14, w1, 3); PIN(pa1); PIN(sacc); PIN(w1); SBAR();
;         } else {
;             LDV(3); PVM(0); E4(0, w0, 0); E4(2, w0, 1); PIN(pa1); PIN(sacc); PIN(w0); SBAR();
;             LDV(4); PVM(1); E4(4, w0, 2); E4(6, w0, 3); PIN(pa1); PIN(sacc); PIN(w0); SBAR();
;             LDV(5); PVM(2); E4(8, w1, 0); E4(10, w1, 1); PIN(pa1); PIN(sacc); PIN(w1); SBAR();
;             LDV(6); PVM(3); E4(12, w1, 2); E4(14, w1, 3); PIN(pa1); PIN(sacc); PIN(w1); SBAR();
;         }
;     ...
;         pw[2] = __builtin_bit_cast(bf16x8, w0); pw[3] = __builtin_bit_cast(bf16x8, w1);
;         lsum += sacc;
;         ATT_FIX(pb0, pb1, ATT_TILE(i + 1));
.Lct2x_nd1:
	v_exp_f32_e32 v98, v98
	v_exp_f32_e32 v99, v99
	v_add_f32_e32 v151, v174, v98
	v_add_f32_e32 v174, v99, v151
	v_cvt_pk_bf16_f32 v151, v98, v99
	ds_read_b64_tr_b16 v[92:93], v164 offset:17408
	ds_read_b64_tr_b16 v[94:95], v164 offset:17920
	v_mfma_f32_32x32x16_bf16 v[116:131], v[190:193], v[0:3], v[116:131]
	v_exp_f32_e32 v100, v100
	v_exp_f32_e32 v101, v101
	v_exp_f32_e32 v102, v102
	v_exp_f32_e32 v103, v103
	v_cvt_pk_bf16_f32 v190, v100, v101
	v_mfma_f32_32x32x16_bf16 v[4:19], v[196:199], v[0:3], v[4:19]
	ds_read_b64_tr_b16 v[68:69], v164 offset:21504
	ds_read_b64_tr_b16 v[70:71], v164 offset:22016
	s_waitcnt lgkmcnt(6)
	v_mfma_f32_32x32x16_bf16 v[52:67], v[72:75], v[152:155], v[52:67]
	v_add_f32_e32 v72, v100, v174
	v_add_f32_e32 v76, v101, v72
	v_add_f32_e32 v73, v102, v76
	v_add_f32_e32 v76, v103, v73
	v_cvt_pk_bf16_f32 v191, v102, v103
	v_exp_f32_e32 v104, v104
	v_exp_f32_e32 v105, v105
	s_waitcnt lgkmcnt(4)
	v_mfma_f32_32x32x16_bf16 v[36:51], v[80:83], v[152:155], v[36:51]
	s_cmp_eq_u32 s27, 0
	s_cbranch_scc1 .Lct2x_nd2
	s_and_b64 vcc, exec, s[42:43]
	s_cbranch_vccnz .Lct2x_nd2
	s_lshl_b64 s[38:39], s[20:21], 10
	s_add_i32 m0, s30, 0x8000
	v_lshl_add_u64 v[182:183], v[160:161], 0, s[38:39]
	global_load_lds_dwordx4 v[182:183], off
.Lct2x_nd2:
	v_exp_f32_e32 v106, v106
	v_exp_f32_e32 v107, v107
	v_add_f32_e32 v74, v76, v104
	ds_read_b64_tr_b16 v[84:85], v164 offset:18432
	ds_read_b64_tr_b16 v[86:87], v164 offset:18944
	v_add_f32_e32 v75, v105, v74
	v_add_f32_e32 v75, v106, v75
	v_cvt_pk_bf16_f32 v192, v104, v105
	v_add_f32_e32 v76, v107, v75
	v_cvt_pk_bf16_f32 v193, v106, v107
	v_exp_f32_e32 v108, v108
	s_waitcnt lgkmcnt(4)
	v_mfma_f32_32x32x16_bf16 v[52:67], v[92:95], v[148:151], v[52:67]
	v_exp_f32_e32 v109, v109
	v_exp_f32_e32 v110, v110
	ds_read_b64_tr_b16 v[88:89], v164 offset:22528
	ds_read_b64_tr_b16 v[90:91], v164 offset:23040
	v_exp_f32_e32 v111, v111
	v_add_f32_e32 v72, v76, v108
	v_add_f32_e32 v76, v109, v72
	v_cvt_pk_bf16_f32 v152, v108, v109
	v_add_f32_e32 v73, v110, v76
	v_add_f32_e32 v76, v111, v73
	v_cvt_pk_bf16_f32 v153, v110, v111
	s_waitcnt lgkmcnt(4)
	v_mfma_f32_32x32x16_bf16 v[36:51], v[68:71], v[148:151], v[36:51]
	v_exp_f32_e32 v112, v112
	v_exp_f32_e32 v113, v113
	v_exp_f32_e32 v114, v114
	v_exp_f32_e32 v115, v115
	ds_read_b64_tr_b16 v[92:93], v164 offset:19456
	ds_read_b64_tr_b16 v[94:95], v164 offset:19968
	v_add_f32_e32 v68, v76, v112
	v_add_f32_e32 v68, v113, v68
	v_cvt_pk_bf16_f32 v154, v112, v113
	v_cvt_pk_bf16_f32 v155, v114, v115
	v_add_f32_e32 v68, v114, v68
	v_add_f32_e32 v68, v115, v68
	s_cmp_lg_u32 s22, s35
	s_cbranch_scc1 .Lct2_357
	v_cndmask_b32_e64 v100, v116, v245, s[48:49]
	v_cndmask_b32_e64 v4, v4, v245, s[50:51]
	v_cndmask_b32_e64 v117, v245, v117, s[52:53]
	v_cndmask_b32_e64 v116, v100, v116, s[52:53]
	v_cndmask_b32_e64 v5, v5, v245, s[54:55]
	v_cndmask_b32_e64 v118, v118, v245, s[56:57]
	v_cndmask_b32_e64 v6, v6, v245, s[58:59]
	v_cndmask_b32_e64 v119, v119, v245, s[60:61]
	v_cndmask_b32_e64 v7, v7, v245, s[62:63]
	v_cndmask_b32_e64 v120, v120, v245, s[64:65]
	v_cndmask_b32_e64 v8, v8, v245, s[66:67]
	v_cndmask_b32_e64 v121, v121, v245, s[68:69]
	v_cndmask_b32_e64 v9, v9, v245, s[70:71]
	v_cndmask_b32_e64 v122, v122, v245, s[72:73]
	v_cndmask_b32_e64 v10, v10, v245, s[74:75]
	v_cndmask_b32_e64 v123, v123, v245, s[76:77]
	v_cndmask_b32_e64 v11, v11, v245, s[78:79]
	v_cndmask_b32_e64 v124, v124, v245, s[80:81]
	v_cndmask_b32_e64 v12, v12, v245, s[82:83]
	v_cndmask_b32_e64 v125, v125, v245, s[84:85]
	v_cndmask_b32_e64 v13, v13, v245, s[86:87]
	v_cndmask_b32_e64 v126, v126, v245, s[88:89]
	v_cndmask_b32_e64 v14, v14, v245, s[90:91]
	v_cndmask_b32_e64 v127, v127, v245, s[92:93]
	v_cndmask_b32_e64 v15, v15, v245, s[94:95]
	v_cndmask_b32_e64 v128, v128, v245, s[96:97]
	v_cndmask_b32_e64 v16, v16, v245, s[4:5]
	v_cndmask_b32_e64 v129, v129, v245, s[6:7]
	v_cndmask_b32_e64 v17, v17, v245, s[8:9]
	v_cndmask_b32_e64 v130, v130, v245, s[10:11]
	v_cndmask_b32_e64 v18, v18, v245, s[12:13]
	v_cndmask_b32_e64 v131, v131, v245, s[14:15]
	v_cndmask_b32_e64 v19, v19, v245, s[16:17]
